# v99 + P4 work queue: thread 0 issues the queue atomic before the loop-top barrier so its round trip overlaps the rendezvous
# speedup vs baseline: 1.0009x; 1.0009x over previous
.LBB0_850:
	s_and_saveexec_b64 s[6:7], s[4:5]
	s_cbranch_execz .Lq_bar
	s_mov_b64 s[10:11], exec
	v_mbcnt_lo_u32_b32 v1, s10, 0
	v_mbcnt_hi_u32_b32 v1, s11, v1
	v_cmp_eq_u32_e32 vcc, 0, v1
	s_and_saveexec_b64 s[8:9], vcc
	s_cbranch_execz .LBB0_853
	s_bcnt1_i32_b64 s2, s[10:11]
	v_mov_b32_e32 v2, s2
	global_atomic_add v2, v0, v2, s[66:67] sc0

.Lq_bar:
	s_barrier
	s_cbranch_execz .LBB0_854
	s_waitcnt vmcnt(0)
	v_readfirstlane_b32 s2, v2
	s_nop 1
	v_add_u32_e32 v1, s2, v1
	ds_write_b32 v0, v1 offset:16
